# v055 plus dequeue prefetch extended to the late weight-transpose queue items (atomic issued at item start, head waits vmcnt(0) for wave 0 only)
# baseline (speedup 1.0000x reference)
; __global__ void __launch_bounds__(512) fwd_kernel(Params P) {
;     ...
;         for (;;) {
;             __syncthreads();
;             if (tid == 0) qs_[0] = (int)atomicAdd(CTL + CW_Q3 + REPQ, 1u);
;             __syncthreads();
;             const int u = qs_[0];
.Lq_pref:
	s_cmp_eq_u32 s98, 2
	s_mov_b32 s98, 0
	s_cbranch_scc1 .Lq_pref2
	s_barrier
	s_mov_b64 s[0:1], exec
	v_readlane_b32 s2, v251, 20
	v_readlane_b32 s3, v251, 21
	s_and_b64 s[2:3], s[0:1], s[2:3]
	s_mov_b64 exec, s[2:3]
	s_cbranch_execz .LBB0_472
	s_waitcnt vmcnt(8)
	ds_write_b32 v1, v249 offset:37632
	s_branch .LBB0_472
.Lq_pref2:
	s_barrier
	s_mov_b64 s[0:1], exec
	v_readlane_b32 s2, v251, 20
	v_readlane_b32 s3, v251, 21
	s_and_b64 s[2:3], s[0:1], s[2:3]
	s_mov_b64 exec, s[2:3]
	s_cbranch_execz .LBB0_472
	s_waitcnt vmcnt(0)
	ds_write_b32 v1, v249 offset:37632
	s_branch .LBB0_472

; #define LAS __attribute__((address_space(3)))
; DI int transposes_total(bool late) { int total = 0; for (int s = 0; s < NSEG; ++s) if (seg_late(s) == late) total += (SEGS[s].K / 64) * ((SEGS[s].len + 31) / 32); return total; }
; DI void transpose_by_index(const Params& P, unsigned char* ws, LAS float* scr, int idx, bool late, int lane) {
;     int rem = idx, s = 0;
;     for (; s < NSEG; ++s) { if (seg_late(s) != late) continue; const int n = (SEGS[s].K / 64) * ((SEGS[s].len + 31) / 32); if (rem < n) break; rem -= n; }
;     const Seg sg = SEGS[s]; const int nnb = (sg.len + 31) / 32;
; __global__ void __launch_bounds__(512) fwd_kernel(Params P) {
;     ...
;             if (tid == 0) qs_[0] = (int)atomicAdd(CTL + CW_Q3 + REPQ, 1u);
;             __syncthreads();
;             const int u = qs_[0];
;             const int nlate = transposes_total(true), nlate_wg = (nlate + 7) >> 3;
;             if (u >= 128 + 2048 + nlate_wg) break;
;             if (u >= 128 + 2048) {
;                 const int idx = (u - (128 + 2048)) * 8 + wid;
;                 if (idx < nlate) transpose_by_index(P, ws, (LAS float*)(L + 40960 + wid * 8448), idx, true, lane);
.LBB0_634:
	s_andn2_b64 vcc, exec, s[2:3]
	s_cbranch_vccnz .LBB0_466
	s_mov_b64 s[0:1], exec
	v_readlane_b32 s2, v251, 20
	v_readlane_b32 s3, v251, 21
	s_and_b64 s[2:3], s[0:1], s[2:3]
	s_mov_b64 exec, s[2:3]
	s_cbranch_execz .Lq_site2_skip
	v_mov_b32_e32 v249, 1
	global_atomic_add v249, v1, v249, s[34:35] sc0
.Lq_site2_skip:
	s_mov_b64 exec, s[0:1]
	s_mov_b32 s98, 2
	s_lshl_b32 s0, s7, 3
	v_readlane_b32 s1, v250, 9
	s_add_i32 s30, s1, s0
	v_readlane_b32 s0, v251, 56
	s_cmp_ge_i32 s30, s0
	s_cbranch_scc1 .LBB0_465
	s_cmp_lt_i32 s30, s64
	s_mov_b64 s[0:1], 11
	s_cbranch_scc1 .LBB0_647
	s_sub_i32 s30, s30, s64
	s_cmp_lt_i32 s30, s65
	s_mov_b64 s[0:1], 12
	s_cbranch_scc1 .LBB0_648
	s_sub_i32 s30, s30, s65
	s_cmp_lt_i32 s30, s74
	s_mov_b64 s[0:1], 13
	s_cbranch_scc1 .LBB0_649
	s_sub_i32 s30, s30, s74
	s_cmp_lt_i32 s30, s75
	s_mov_b64 s[0:1], 14
	s_cbranch_scc1 .LBB0_650
	s_sub_i32 s30, s30, s75
	s_cmp_lt_i32 s30, s81
	s_mov_b64 s[0:1], 15
	s_cbranch_scc1 .LBB0_651
	s_sub_i32 s30, s30, s81
	s_cmp_lt_i32 s30, s91
	s_mov_b64 s[0:1], 18
	s_cbranch_scc1 .LBB0_652
	s_sub_i32 s30, s30, s91
	s_cmp_lt_i32 s30, s92
	s_mov_b64 s[0:1], 19
	s_cbranch_scc1 .LBB0_653
	s_sub_i32 s30, s30, s92
	s_cmp_lt_i32 s30, s87
	s_mov_b64 s[0:1], 20
	s_cbranch_scc1 .LBB0_654
	s_sub_i32 s30, s30, s87
	s_cmp_lt_i32 s30, s88
	s_mov_b64 s[0:1], 21
	s_cbranch_scc1 .LBB0_655
	s_sub_i32 s30, s30, s88
	s_cmp_lt_i32 s30, s89
	s_mov_b64 s[0:1], 22
	s_cbranch_scc1 .LBB0_656
	s_sub_i32 s30, s30, s89
	s_mov_b64 s[0:1], 23
	v_readlane_b32 s7, v251, 55
	s_branch .LBB0_657
